# prologue weight transposes (gain-folded w_in/w_up): all 8 rows + 8 gains of a tile loaded together instead of one dependent pair at a time
# speedup vs baseline: 1.0078x; 1.0034x over previous
; #define LAS __attribute__((address_space(3)))
; DI unsigned pk(float lo, float hi) { return pg8::cvt_pk_bf16(lo, hi); }
; DI void transpose_w(const float* W, bf16* Bt, int K, int N, int mode, const float* rowgain, LAS float* tile, int bid, int nb, int tid) {
;     const int tk = K / 64, tn = N / 64;
;     for (int t = bid; t < tk * tn; t += nb) {
;         const int k0 = (t % tk) * 64, n0 = (t / tk) * 64;
;         int ns0 = n0; if (mode) { const int pn = n0 >> 8, jj = n0 & 255; ns0 = (jj < 128) ? pn * 128 + jj : DFF + pn * 128 + (jj - 128); }
; #pragma unroll
;         for (int it = 0; it < 8; ++it) { const int r = (tid >> 6) + 8 * it, cc = tid & 63; tile[r * 65 + cc] = W[(size_t)(k0 + r) * N + ns0 + cc] * (rowgain ? rowgain[k0 + r] : 1.0f); }
;         __syncthreads();
; #pragma unroll
;         for (int it = 0; it < 4; ++it) { const int nn = (tid >> 5) + 16 * it, kp = tid & 31;
;             *(unsigned*)(Bt + (size_t)(n0 + nn) * K + k0 + 2 * kp) = pk(tile[(2 * kp) * 65 + nn], tile[(2 * kp + 1) * 65 + nn]); }
;         __syncthreads();
;     }
.LBB0_9:
	s_waitcnt lgkmcnt(0)
	s_barrier
	ds_read2_b32 v[22:23], v31 offset1:16
	ds_read2_b32 v[24:25], v31 offset0:65 offset1:81
	s_sub_i32 s4, 0, s38
	s_add_i32 s4, s35, s4
	v_add_u32_e32 v38, s28, v30
	s_ashr_i32 s5, s4, 31
	v_ashrrev_i32_e32 v39, 31, v38
	v_lshl_add_u64 v[26:27], s[4:5], 1, v[20:21]
	v_lshlrev_b64 v[38:39], 11, v[38:39]
	s_waitcnt lgkmcnt(0)
	v_cvt_pk_bf16_f32 v22, v22, v24
	v_lshl_add_u64 v[38:39], v[26:27], 0, v[38:39]
	global_store_dword v[38:39], v22, off
	v_add_u32_e32 v22, s28, v32
	v_cvt_pk_bf16_f32 v37, v23, v25
	v_ashrrev_i32_e32 v23, 31, v22
	ds_read2_b32 v[24:25], v31 offset0:32 offset1:48
	ds_read2_b32 v[38:39], v31 offset0:97 offset1:113
	v_lshlrev_b64 v[22:23], 11, v[22:23]
	v_lshl_add_u64 v[22:23], v[26:27], 0, v[22:23]
	global_store_dword v[22:23], v37, off
	v_add_u32_e32 v22, s28, v33
	v_ashrrev_i32_e32 v23, 31, v22
	v_lshlrev_b64 v[22:23], 11, v[22:23]
	s_waitcnt lgkmcnt(0)
	v_cvt_pk_bf16_f32 v24, v24, v38
	v_lshl_add_u64 v[22:23], v[26:27], 0, v[22:23]
	global_store_dword v[22:23], v24, off
	v_add_u32_e32 v22, s28, v34
	v_ashrrev_i32_e32 v23, 31, v22
	v_lshlrev_b64 v[22:23], 11, v[22:23]
	s_add_i32 s37, s37, s87
	s_add_i32 s35, s35, s36
	v_cvt_pk_bf16_f32 v24, v25, v39
	v_lshl_add_u64 v[22:23], v[26:27], 0, v[22:23]
	s_cmpk_lt_i32 s37, 0x400
	global_store_dword v[22:23], v24, off
	s_barrier
	s_cbranch_scc0 .LBB0_26
.LBB0_10:
	s_ashr_i32 s4, s37, 31
	s_lshr_b32 s4, s4, 28
	s_add_i32 s4, s37, s4
	s_ashr_i32 s4, s4, 4
	s_lshl_b32 s38, s4, 10
	s_lshl_b32 s28, s4, 6
	s_sub_i32 s4, s35, s38
	v_add_u32_e32 v26, s4, v29
	s_ashr_i32 s29, s28, 31
	v_ashrrev_i32_e32 v27, 31, v26
	v_lshl_add_u64 v[22:23], s[28:29], 2, v[18:19]
	v_lshlrev_b64 v[24:25], 14, v[26:27]
	v_lshl_add_u64 v[24:25], v[22:23], 0, v[24:25]
	global_load_dword v52, v[24:25], off
	s_mov_b64 s[98:99], 0x20000
	v_lshl_add_u64 v[68:69], s[98:99], 0, v[24:25]
	global_load_dword v53, v[68:69], off
	v_lshl_add_u64 v[68:69], s[98:99], 0, v[68:69]
	global_load_dword v54, v[68:69], off
	v_lshl_add_u64 v[68:69], s[98:99], 0, v[68:69]
	global_load_dword v55, v[68:69], off
	v_lshl_add_u64 v[68:69], s[98:99], 0, v[68:69]
	global_load_dword v56, v[68:69], off
	v_lshl_add_u64 v[68:69], s[98:99], 0, v[68:69]
	global_load_dword v57, v[68:69], off
	v_lshl_add_u64 v[68:69], s[98:99], 0, v[68:69]
	global_load_dword v58, v[68:69], off
	v_lshl_add_u64 v[68:69], s[98:99], 0, v[68:69]
	global_load_dword v59, v[68:69], off
	v_mov_b32_e32 v60, 1.0
	v_mov_b32_e32 v61, 1.0
	v_mov_b32_e32 v62, 1.0
	v_mov_b32_e32 v63, 1.0
	v_mov_b32_e32 v64, 1.0
	v_mov_b32_e32 v65, 1.0
	v_mov_b32_e32 v66, 1.0
	v_mov_b32_e32 v67, 1.0
	v_lshl_add_u64 v[24:25], v[26:27], 2, s[26:27]
	s_andn2_b64 vcc, exec, s[18:19]
	s_cbranch_vccnz .Ltr_nogain_win
	global_load_dword v60, v[24:25], off
	global_load_dword v61, v[24:25], off offset:32
	global_load_dword v62, v[24:25], off offset:64
	global_load_dword v63, v[24:25], off offset:96
	global_load_dword v64, v[24:25], off offset:128
	global_load_dword v65, v[24:25], off offset:160
	global_load_dword v66, v[24:25], off offset:192
	global_load_dword v67, v[24:25], off offset:224
.Ltr_nogain_win:
	s_waitcnt vmcnt(0)
	v_mul_f32_e32 v52, v52, v60
	ds_write_b32 v36, v52
	v_mul_f32_e32 v53, v53, v61
	ds_write_b32 v36, v53 offset:2080
	v_mul_f32_e32 v54, v54, v62
	ds_write_b32 v36, v54 offset:4160
	v_mul_f32_e32 v55, v55, v63
	ds_write_b32 v36, v55 offset:6240
	v_mul_f32_e32 v56, v56, v64
	ds_write_b32 v36, v56 offset:8320
	v_mul_f32_e32 v57, v57, v65
	ds_write_b32 v36, v57 offset:10400
	v_mul_f32_e32 v58, v58, v66
	ds_write_b32 v36, v58 offset:12480
	v_mul_f32_e32 v59, v59, v67
	ds_write_b32 v36, v59 offset:14560
	s_branch .LBB0_9

; #define LAS __attribute__((address_space(3)))
; DI unsigned pk(float lo, float hi) { return pg8::cvt_pk_bf16(lo, hi); }
; DI void transpose_w(const float* W, bf16* Bt, int K, int N, int mode, const float* rowgain, LAS float* tile, int bid, int nb, int tid) {
;     const int tk = K / 64, tn = N / 64;
;     for (int t = bid; t < tk * tn; t += nb) {
;         const int k0 = (t % tk) * 64, n0 = (t / tk) * 64;
;         int ns0 = n0; if (mode) { const int pn = n0 >> 8, jj = n0 & 255; ns0 = (jj < 128) ? pn * 128 + jj : DFF + pn * 128 + (jj - 128); }
; #pragma unroll
;         for (int it = 0; it < 8; ++it) { const int r = (tid >> 6) + 8 * it, cc = tid & 63; tile[r * 65 + cc] = W[(size_t)(k0 + r) * N + ns0 + cc] * (rowgain ? rowgain[k0 + r] : 1.0f); }
;         __syncthreads();
; #pragma unroll
;         for (int it = 0; it < 4; ++it) { const int nn = (tid >> 5) + 16 * it, kp = tid & 31;
;             *(unsigned*)(Bt + (size_t)(n0 + nn) * K + k0 + 2 * kp) = pk(tile[(2 * kp) * 65 + nn], tile[(2 * kp + 1) * 65 + nn]); }
;         __syncthreads();
;     }
.LBB0_31:
	s_waitcnt lgkmcnt(0)
	s_barrier
	ds_read2_b32 v[22:23], v31 offset1:16
	ds_read2_b32 v[24:25], v31 offset0:65 offset1:81
	s_sub_i32 s4, 0, s37
	s_add_i32 s4, s28, s4
	v_add_u32_e32 v38, s36, v30
	s_ashr_i32 s5, s4, 31
	v_ashrrev_i32_e32 v39, 31, v38
	v_lshl_add_u64 v[26:27], s[4:5], 1, v[20:21]
	v_lshlrev_b64 v[38:39], 11, v[38:39]
	s_waitcnt lgkmcnt(0)
	v_cvt_pk_bf16_f32 v22, v22, v24
	v_lshl_add_u64 v[38:39], v[26:27], 0, v[38:39]
	global_store_dword v[38:39], v22, off
	v_add_u32_e32 v22, s36, v32
	v_cvt_pk_bf16_f32 v37, v23, v25
	v_ashrrev_i32_e32 v23, 31, v22
	ds_read2_b32 v[24:25], v31 offset0:32 offset1:48
	ds_read2_b32 v[38:39], v31 offset0:97 offset1:113
	v_lshlrev_b64 v[22:23], 11, v[22:23]
	v_lshl_add_u64 v[22:23], v[26:27], 0, v[22:23]
	global_store_dword v[22:23], v37, off
	v_add_u32_e32 v22, s36, v33
	v_ashrrev_i32_e32 v23, 31, v22
	v_lshlrev_b64 v[22:23], 11, v[22:23]
	s_waitcnt lgkmcnt(0)
	v_cvt_pk_bf16_f32 v24, v24, v38
	v_lshl_add_u64 v[22:23], v[26:27], 0, v[22:23]
	global_store_dword v[22:23], v24, off
	v_add_u32_e32 v22, s36, v34
	v_ashrrev_i32_e32 v23, 31, v22
	v_lshlrev_b64 v[22:23], 11, v[22:23]
	s_add_i32 s35, s35, s87
	s_add_i32 s28, s28, s29
	v_cvt_pk_bf16_f32 v24, v25, v39
	v_lshl_add_u64 v[22:23], v[26:27], 0, v[22:23]
	s_cmpk_lt_i32 s35, 0x580
	global_store_dword v[22:23], v24, off
	s_barrier
	s_cbranch_scc0 .LBB0_48
.LBB0_32:
	s_ashr_i32 s4, s35, 31
	s_lshr_b32 s4, s4, 28
	s_add_i32 s4, s35, s4
	s_ashr_i32 s4, s4, 4
	s_lshl_b32 s37, s4, 10
	s_lshl_b32 s36, s4, 6
	s_lshl_b32 s4, s4, 5
	s_and_b32 s5, s36, 0xc0
	s_and_b32 s4, s4, 0xffffff80
	s_or_b32 s38, s4, s5
	s_add_i32 s4, s5, s4
	s_addk_i32 s4, 0xa80
	s_cmpk_lt_u32 s5, 0x80
	s_cselect_b32 s4, s38, s4
	s_ashr_i32 s5, s4, 31
	v_lshl_add_u64 v[22:23], s[4:5], 2, v[18:19]
	s_sub_i32 s4, s28, s37
	v_add_u32_e32 v24, s4, v29
	v_mad_i64_i32 v[26:27], s[4:5], v24, s30, v[22:23]
	global_load_dword v52, v[26:27], off
	s_lshl_b32 s98, s30, 3
	s_mov_b32 s99, 0
	v_lshl_add_u64 v[68:69], s[98:99], 0, v[26:27]
	global_load_dword v53, v[68:69], off
	v_lshl_add_u64 v[68:69], s[98:99], 0, v[68:69]
	global_load_dword v54, v[68:69], off
	v_lshl_add_u64 v[68:69], s[98:99], 0, v[68:69]
	global_load_dword v55, v[68:69], off
	v_lshl_add_u64 v[68:69], s[98:99], 0, v[68:69]
	global_load_dword v56, v[68:69], off
	v_lshl_add_u64 v[68:69], s[98:99], 0, v[68:69]
	global_load_dword v57, v[68:69], off
	v_lshl_add_u64 v[68:69], s[98:99], 0, v[68:69]
	global_load_dword v58, v[68:69], off
	v_lshl_add_u64 v[68:69], s[98:99], 0, v[68:69]
	global_load_dword v59, v[68:69], off
	v_mov_b32_e32 v60, 1.0
	v_mov_b32_e32 v61, 1.0
	v_mov_b32_e32 v62, 1.0
	v_mov_b32_e32 v63, 1.0
	v_mov_b32_e32 v64, 1.0
	v_mov_b32_e32 v65, 1.0
	v_mov_b32_e32 v66, 1.0
	v_mov_b32_e32 v67, 1.0
	v_ashrrev_i32_e32 v25, 31, v24
	v_lshl_add_u64 v[26:27], v[24:25], 2, s[24:25]
	s_andn2_b64 vcc, exec, s[20:21]
	s_cbranch_vccnz .Ltr_nogain_wup
	global_load_dword v60, v[26:27], off
	global_load_dword v61, v[26:27], off offset:32
	global_load_dword v62, v[26:27], off offset:64
	global_load_dword v63, v[26:27], off offset:96
	global_load_dword v64, v[26:27], off offset:128
	global_load_dword v65, v[26:27], off offset:160
	global_load_dword v66, v[26:27], off offset:192
	global_load_dword v67, v[26:27], off offset:224
